# weight copies of Wa/Wb/Wo, ffn2 w1/w3, ffn2 w2 moved from P4b into idle workgroups of the last GEMM round of P1/P3/P7
# speedup vs baseline: 1.0003x; 1.0003x over previous
; #define GAS __attribute__((address_space(1)))
; #define LAS __attribute__((address_space(3)))
; #define LDS_WAIT() asm volatile("s_waitcnt lgkmcnt(0)" ::: "memory")
; __device__ __forceinline__ unsigned pk2(float lo, float hi) { const f32x2_t_ v = {lo, hi}; return __builtin_bit_cast(unsigned, __builtin_convertvector(v, bf16x2_t_)); }
; __device__ __forceinline__ void transpose_item(const float* W, const float* g, int ldw, int K, int ncols, bf16* WT, int mode, int roff, LAS float* scr, int item, int lane) {
;     const int nblk = ncols / 32, kb = item / nblk, nb = item % nblk, k0 = 64 * kb, n0 = 32 * nb;
;     const float g0 = g ? g[k0 + lane] : 1.0f;
; #pragma unroll 8
;     for (int i = 0; i < 32; ++i) { const int kk = 2 * i + (lane >> 5); scr[kk * 33 + (lane & 31)] = W[(size_t)(k0 + kk) * ldw + n0 + (lane & 31)] * __shfl(g0, kk); }
;     LDS_WAIT(); asm volatile("" ::: "memory");
;     const int c = lane & 7;
; #pragma unroll
;     for (int j = 0; j < 4; ++j) { const int n = (lane >> 3) + 8 * j; const LAS float* s = scr + (8 * c) * 33 + n;
;         v4u o; o.x = pk2(s[0 * 33], s[1 * 33]); o.y = pk2(s[2 * 33], s[3 * 33]); o.z = pk2(s[4 * 33], s[5 * 33]); o.w = pk2(s[6 * 33], s[7 * 33]);
;         const int jc = n0 + n; const int drow = mode ? roff + ((jc >> 4) << 5) + (jc & 15) : roff + jc;
;         *(GAS v4u*)(WT + (size_t)drow * K + k0 + 8 * c) = o; }
;     LDS_WAIT(); asm volatile("" ::: "memory");
; }
; __device__ __forceinline__ void conv_mat(const float* W, const float* g, int ldw, int K, int ncols, bf16* WT, int mode, int roff, LAS float* scr, int lane, int gw, int NGW) {
;     const int nitems = (K / 64) * (ncols / 32);
;     for (int it = gw; it < nitems; it += NGW) transpose_item(W, g, ldw, K, ncols, WT, mode, roff, scr, it, lane);
; __global__ void __launch_bounds__(NWAVES * 64, 2) mk_fwd(Args args) {
;     ...
;     const int first_idle = 1496 % F.G, n_idle = first_idle ? F.G - first_idle : F.G, my_idle = first_idle ? (int)blockIdx.x - first_idle : (int)blockIdx.x;
;     const int INGW = n_idle * NWAVES;
.LBB0_377:
	s_cmpk_lt_i32 s2, 0xd8
	s_cbranch_scc1 .Lcm_p1t_skip
	s_mov_b64 exec, -1
	v_readfirstlane_b32 s3, v0
	s_lshr_b32 s3, s3, 6
	s_lshl_b32 s12, s3, 14
	s_sub_i32 s10, s2, 0xd8
	s_lshl_b32 s10, s10, 3
	s_add_i32 s10, s10, s3
	s_sub_i32 s11, s18, 0xd8
	s_lshl_b32 s11, s11, 3
	v_and_b32_e32 v15, 63, v0
	v_lshrrev_b32_e32 v2, 3, v15
	v_and_b32_e32 v3, 7, v15
	v_lshlrev_b32_e32 v3, 4, v3
	v_mul_u32_u24_e32 v4, 0x84, v2
	v_add3_u32 v4, v4, v3, s12
	v_and_b32_e32 v5, 7, v15
	v_mul_u32_u24_e32 v5, 0x420, v5
	v_lshl_add_u32 v5, v2, 2, v5
	v_add_u32_e32 v5, s12, v5
	v_add_u32_e32 v6, 0, v2
	v_lshrrev_b32_e32 v10, 4, v6
	v_lshlrev_b32_e32 v10, 5, v10
	v_and_b32_e32 v14, 15, v6
	v_or_b32_e32 v10, v10, v14
	v_add_u32_e32 v7, 8, v2
	v_lshrrev_b32_e32 v11, 4, v7
	v_lshlrev_b32_e32 v11, 5, v11
	v_and_b32_e32 v14, 15, v7
	v_or_b32_e32 v11, v11, v14
	v_add_u32_e32 v8, 16, v2
	v_lshrrev_b32_e32 v12, 4, v8
	v_lshlrev_b32_e32 v12, 5, v12
	v_and_b32_e32 v14, 15, v8
	v_or_b32_e32 v12, v12, v14
	v_add_u32_e32 v9, 24, v2
	v_lshrrev_b32_e32 v13, 4, v9
	v_lshlrev_b32_e32 v13, 5, v13
	v_and_b32_e32 v14, 15, v9
	v_or_b32_e32 v13, v13, v14
	s_cmp_lt_u32 s10, 1024
	s_cbranch_scc0 .Lcw_p1t_done
	s_cmp_lt_u32 s10, 256
	s_cbranch_scc1 .Lcw_p1t_i0_c0
	s_cmp_lt_u32 s10, 512
	s_cbranch_scc1 .Lcw_p1t_i0_c1

; #define LAS __attribute__((address_space(3)))
; __device__ __forceinline__ void conv_mat(const float* W, const float* g, int ldw, int K, int ncols, bf16* WT, int mode, int roff, LAS float* scr, int lane, int gw, int NGW) {
;     const int nitems = (K / 64) * (ncols / 32);
;     for (int it = gw; it < nitems; it += NGW) transpose_item(W, g, ldw, K, ncols, WT, mode, roff, scr, it, lane);
.Lcw_p1t_loop:
	s_add_u32 s10, s10, s11
	s_cmp_lt_u32 s10, 1024
	s_cbranch_scc0 .Lcw_p1t_lastA
	s_cmp_lt_u32 s10, 256
	s_cbranch_scc1 .Lcw_p1t_i1_c0
	s_cmp_lt_u32 s10, 512
	s_cbranch_scc1 .Lcw_p1t_i1_c1

; #define GAS __attribute__((address_space(1)))
; #define LAS __attribute__((address_space(3)))
; #define LDS_WAIT() asm volatile("s_waitcnt lgkmcnt(0)" ::: "memory")
; __device__ __forceinline__ unsigned pk2(float lo, float hi) { const f32x2_t_ v = {lo, hi}; return __builtin_bit_cast(unsigned, __builtin_convertvector(v, bf16x2_t_)); }
; __device__ __forceinline__ void transpose_item(const float* W, const float* g, int ldw, int K, int ncols, bf16* WT, int mode, int roff, LAS float* scr, int item, int lane) {
;     ...
;     for (int i = 0; i < 32; ++i) { const int kk = 2 * i + (lane >> 5); scr[kk * 33 + (lane & 31)] = W[(size_t)(k0 + kk) * ldw + n0 + (lane & 31)] * __shfl(g0, kk); }
;     LDS_WAIT(); asm volatile("" ::: "memory");
;     const int c = lane & 7;
; #pragma unroll
;     for (int j = 0; j < 4; ++j) { const int n = (lane >> 3) + 8 * j; const LAS float* s = scr + (8 * c) * 33 + n;
;         v4u o; o.x = pk2(s[0 * 33], s[1 * 33]); o.y = pk2(s[2 * 33], s[3 * 33]); o.z = pk2(s[4 * 33], s[5 * 33]); o.w = pk2(s[6 * 33], s[7 * 33]);
;         const int jc = n0 + n; const int drow = mode ? roff + ((jc >> 4) << 5) + (jc & 15) : roff + jc;
;         *(GAS v4u*)(WT + (size_t)drow * K + k0 + 8 * c) = o; }
;     LDS_WAIT(); asm volatile("" ::: "memory");
.Lcw_p1t_pA:
	s_mov_b32 s13, 0
	ds_write_b32 v4, v16
	ds_write_b32 v4, v17 offset:4
	ds_write_b32 v4, v18 offset:8
	ds_write_b32 v4, v19 offset:12
	ds_write_b32 v4, v20 offset:1056
	ds_write_b32 v4, v21 offset:1060
	ds_write_b32 v4, v22 offset:1064
	ds_write_b32 v4, v23 offset:1068
	ds_write_b32 v4, v24 offset:2112
	ds_write_b32 v4, v25 offset:2116
	ds_write_b32 v4, v26 offset:2120
	ds_write_b32 v4, v27 offset:2124
	ds_write_b32 v4, v28 offset:3168
	ds_write_b32 v4, v29 offset:3172
	ds_write_b32 v4, v30 offset:3176
	ds_write_b32 v4, v31 offset:3180
	ds_write_b32 v4, v32 offset:4224
	ds_write_b32 v4, v33 offset:4228
	ds_write_b32 v4, v34 offset:4232
	ds_write_b32 v4, v35 offset:4236
	ds_write_b32 v4, v36 offset:5280
	ds_write_b32 v4, v37 offset:5284
	ds_write_b32 v4, v38 offset:5288
	ds_write_b32 v4, v39 offset:5292
	ds_write_b32 v4, v40 offset:6336
	ds_write_b32 v4, v41 offset:6340
	ds_write_b32 v4, v42 offset:6344
	ds_write_b32 v4, v43 offset:6348
	ds_write_b32 v4, v44 offset:7392
	ds_write_b32 v4, v45 offset:7396
	ds_write_b32 v4, v46 offset:7400
	ds_write_b32 v4, v47 offset:7404
	v_cndmask_b32_e64 v15, v6, v10, s[38:39]
	v_mad_u32_u24 v128, v15, s36, v3
	v_cndmask_b32_e64 v15, v7, v11, s[38:39]
	v_mad_u32_u24 v129, v15, s36, v3
	v_cndmask_b32_e64 v15, v8, v12, s[38:39]
	v_mad_u32_u24 v130, v15, s36, v3
	v_cndmask_b32_e64 v15, v9, v13, s[38:39]
	v_mad_u32_u24 v131, v15, s36, v3
	s_waitcnt lgkmcnt(0)
	ds_read2_b32 v[80:81], v5 offset0:0 offset1:33
	ds_read2_b32 v[82:83], v5 offset0:66 offset1:99
	ds_read2_b32 v[84:85], v5 offset0:132 offset1:165
	ds_read2_b32 v[86:87], v5 offset0:198 offset1:231
	ds_read2_b32 v[88:89], v5 offset0:8 offset1:41
	ds_read2_b32 v[90:91], v5 offset0:74 offset1:107
	ds_read2_b32 v[92:93], v5 offset0:140 offset1:173
	ds_read2_b32 v[94:95], v5 offset0:206 offset1:239
	ds_read2_b32 v[96:97], v5 offset0:16 offset1:49
	ds_read2_b32 v[98:99], v5 offset0:82 offset1:115
	ds_read2_b32 v[100:101], v5 offset0:148 offset1:181
	ds_read2_b32 v[102:103], v5 offset0:214 offset1:247
	ds_read2_b32 v[104:105], v5 offset0:24 offset1:57
	ds_read2_b32 v[106:107], v5 offset0:90 offset1:123
	ds_read2_b32 v[108:109], v5 offset0:156 offset1:189
	ds_read2_b32 v[110:111], v5 offset0:222 offset1:255
	s_waitcnt lgkmcnt(12)
	v_cvt_pk_bf16_f32 v112, v80, v81
	v_cvt_pk_bf16_f32 v113, v82, v83
	v_cvt_pk_bf16_f32 v114, v84, v85
	v_cvt_pk_bf16_f32 v115, v86, v87
	global_store_dwordx4 v128, v[112:115], s[34:35]
	s_waitcnt lgkmcnt(8)
	v_cvt_pk_bf16_f32 v116, v88, v89
	v_cvt_pk_bf16_f32 v117, v90, v91
	v_cvt_pk_bf16_f32 v118, v92, v93
	v_cvt_pk_bf16_f32 v119, v94, v95
	global_store_dwordx4 v129, v[116:119], s[34:35]
	s_waitcnt lgkmcnt(4)
	v_cvt_pk_bf16_f32 v120, v96, v97
	v_cvt_pk_bf16_f32 v121, v98, v99
	v_cvt_pk_bf16_f32 v122, v100, v101
	v_cvt_pk_bf16_f32 v123, v102, v103
	global_store_dwordx4 v130, v[120:123], s[34:35]
	s_waitcnt lgkmcnt(0)
	v_cvt_pk_bf16_f32 v124, v104, v105
	v_cvt_pk_bf16_f32 v125, v106, v107
	v_cvt_pk_bf16_f32 v126, v108, v109
	v_cvt_pk_bf16_f32 v127, v110, v111
	global_store_dwordx4 v131, v[124:127], s[34:35]
	s_add_u32 s10, s10, s11
	s_cmp_lt_u32 s10, 1024
	s_cbranch_scc0 .Lcw_p1t_lastB
	s_cmp_lt_u32 s10, 256
	s_cbranch_scc1 .Lcw_p1t_i2_c0
	s_cmp_lt_u32 s10, 512
	s_cbranch_scc1 .Lcw_p1t_i2_c1

; __device__ __forceinline__ unsigned xb_ld(unsigned* p)              { return __hip_atomic_load(p, __ATOMIC_RELAXED, __HIP_MEMORY_SCOPE_AGENT); }
; __device__ __forceinline__ unsigned xb_add(unsigned* p, unsigned v) { return __hip_atomic_fetch_add(p, v, __ATOMIC_RELAXED, __HIP_MEMORY_SCOPE_AGENT); }
; __device__ __forceinline__ void xcd_barrier_complete(unsigned* bar, unsigned x, unsigned& nloc, unsigned& nx) {
;     const unsigned G = gridDim.x * gridDim.y * gridDim.z;
;     unsigned sum, cnt, mine, sp = 0u;
;     for (;;) {
;         sum = 0u; cnt = 0u; mine = 0u;
; #pragma unroll
;         for (unsigned j = 0; j < 16; ++j) { const unsigned c = xb_ld(&bar[XB_XCNT(j)]); sum += c; cnt += (c > 0u) ? 1u : 0u; mine = (j == x) ? c : mine; }
; __device__ __forceinline__ void xcd_barrier(const XcdBarrier& b) {
;     asm volatile("s_waitcnt vmcnt(0)" ::: "memory");
;     __syncthreads();
;     if (threadIdx.x == 0) {
;         unsigned* bar = b.bar;
;         __builtin_amdgcn_s_waitcnt(0);
;         unsigned nloc = b.st[0], nx = b.st[1];
;         if (nloc == 0u) { xcd_barrier_complete(bar, b.x, nloc, nx); b.st[0] = nloc; b.st[1] = nx; }
;         const unsigned old = xb_add(&bar[XB_XSUB(b.x)], 1u);
.Lcw_p1t_done:
	s_waitcnt lgkmcnt(0)
.Lcm_p1t_skip:
	s_waitcnt vmcnt(0)
	s_waitcnt vmcnt(0)
	s_barrier
	s_and_saveexec_b64 s[6:7], s[4:5]
	s_cbranch_execz .LBB0_506
	s_add_i32 s3, 0, 0x20160
	v_mov_b32_e32 v1, s3
	s_waitcnt vmcnt(0) expcnt(0) lgkmcnt(0)
	ds_read_b32 v3, v1
	s_add_i32 s3, 0, 0x20164
	v_mov_b32_e32 v1, s3
	ds_read_b32 v1, v1
	s_waitcnt lgkmcnt(1)
	v_cmp_ne_u32_e32 vcc, 0, v3
	s_cbranch_vccnz .LBB0_393
	s_load_dwordx2 s[12:13], s[26:27], 0x4
	s_add_u32 s8, s22, 0x4200
	s_addc_u32 s9, s23, 0
	s_add_u32 s10, s22, 0x4400
	s_addc_u32 s11, s23, 0
	s_waitcnt lgkmcnt(0)
	s_mul_i32 s3, s12, s18
	s_add_u32 s12, s22, 0x4500
	s_mul_i32 s3, s3, s13
	s_addc_u32 s13, s23, 0
	s_add_u32 s14, s22, 0x4600
	s_addc_u32 s15, s23, 0
	s_add_u32 s16, s22, 0x4700
	s_addc_u32 s17, s23, 0
	s_add_u32 s36, s22, 0x4800
	s_addc_u32 s37, s23, 0
	s_add_u32 s38, s22, 0x4900
	s_addc_u32 s39, s23, 0
	s_add_u32 s40, s22, 0x4a00
	s_addc_u32 s41, s23, 0
	s_add_u32 s42, s22, 0x4b00
	s_addc_u32 s43, s23, 0
	s_add_u32 s44, s22, 0x4c00
	s_addc_u32 s45, s23, 0
	s_add_u32 s46, s22, 0x4d00
	s_addc_u32 s47, s23, 0
	s_add_u32 s48, s22, 0x4e00
	s_addc_u32 s49, s23, 0
	s_add_u32 s50, s22, 0x4f00
	s_addc_u32 s51, s23, 0
	s_add_u32 s52, s22, 0x5000
	s_addc_u32 s53, s23, 0
	s_add_u32 s54, s22, 0x5100
	s_addc_u32 s55, s23, 0
	s_add_u32 s56, s22, 0x5200
	s_addc_u32 s57, s23, 0
	s_add_u32 s58, s22, 0x5300
	s_addc_u32 s59, s23, 0
	s_mov_b32 s19, 1
	v_mov_b32_e32 v17, 0
	s_branch .LBB0_381

; #define LAS __attribute__((address_space(3)))
; __device__ __forceinline__ void transpose_item(const float* W, const float* g, int ldw, int K, int ncols, bf16* WT, int mode, int roff, LAS float* scr, int item, int lane) {
;     const int nblk = ncols / 32, kb = item / nblk, nb = item % nblk, k0 = 64 * kb, n0 = 32 * nb;
;     const float g0 = g ? g[k0 + lane] : 1.0f;
; __device__ __forceinline__ void conv_w13(const float* w1, const float* w3, const float* g, unsigned char* ws, LAS float* scr, int lane, int gw, int NGW) {
;     bf16* W13 = (bf16*)(ws + WS_W13);
;     conv_mat(w1, g, DFF, DM, DFF, W13, 1, 0, scr, lane, gw, NGW);
;     conv_mat(w3, g, DFF, DM, DFF, W13, 1, 16, scr, lane, (gw + NGW / 2) % NGW, NGW);
; }
.LBB0_869:
	s_cmpk_lt_i32 s2, 0xd8
	s_cbranch_scc1 .Lcm_p3t_skip
	s_mov_b64 exec, -1
	v_readfirstlane_b32 s3, v0
	s_lshr_b32 s3, s3, 6
	s_lshl_b32 s12, s3, 14
	s_sub_i32 s10, s2, 0xd8
	s_lshl_b32 s10, s10, 3
	s_add_i32 s10, s10, s3
	s_sub_i32 s11, s18, 0xd8
	s_lshl_b32 s11, s11, 3
	v_and_b32_e32 v15, 63, v0
	v_lshrrev_b32_e32 v2, 3, v15
	v_and_b32_e32 v3, 7, v15
	v_lshlrev_b32_e32 v3, 4, v3
	v_mul_u32_u24_e32 v4, 0x84, v2
	v_add3_u32 v4, v4, v3, s12
	v_and_b32_e32 v5, 7, v15
	v_mul_u32_u24_e32 v5, 0x420, v5
	v_lshl_add_u32 v5, v2, 2, v5
	v_add_u32_e32 v5, s12, v5
	v_add_u32_e32 v6, 0, v2
	v_lshrrev_b32_e32 v10, 4, v6
	v_lshlrev_b32_e32 v10, 5, v10
	v_and_b32_e32 v14, 15, v6
	v_or_b32_e32 v10, v10, v14
	v_add_u32_e32 v7, 8, v2
	v_lshrrev_b32_e32 v11, 4, v7
	v_lshlrev_b32_e32 v11, 5, v11
	v_and_b32_e32 v14, 15, v7
	v_or_b32_e32 v11, v11, v14
	v_add_u32_e32 v8, 16, v2
	v_lshrrev_b32_e32 v12, 4, v8
	v_lshlrev_b32_e32 v12, 5, v12
	v_and_b32_e32 v14, 15, v8
	v_or_b32_e32 v12, v12, v14
	v_add_u32_e32 v9, 24, v2
	v_lshrrev_b32_e32 v13, 4, v9
	v_lshlrev_b32_e32 v13, 5, v13
	v_and_b32_e32 v14, 15, v9
	v_or_b32_e32 v13, v13, v14
	s_cmp_lt_u32 s10, 2816
	s_cbranch_scc0 .Lcw_p3t_done
	s_cmp_lt_u32 s10, 1408
	s_cbranch_scc1 .Lcw_p3t_i0_c0
.Lcw_p3t_i0_c1:
	s_load_dwordx2 s[8:9], s[0:1], 0x90
	s_sub_u32 s14, s10, 1408
	s_mul_hi_u32 s15, s14, 0x2e8ba2f
	s_mul_i32 s16, s15, 88
	s_sub_u32 s16, s14, s16
	s_mul_i32 s17, s15, 0xb0000
	s_lshl_b32 s19, s16, 7
	s_add_u32 s17, s17, s19
	s_mov_b32 s3, 0x2c00
	s_mul_i32 s46, s16, 0x20000
	s_lshl_b32 s47, s15, 7
	s_add_u32 s46, s46, s47
	s_add_u32 s46, s46, 0x1008000
	s_add_u32 s34, s22, s46
	s_addc_u32 s35, s23, 0
	s_mov_b32 s36, 0x800
	s_mov_b64 s[38:39], -1
	s_branch .Lcw_p3t_i0_go
.Lcw_p3t_i0_c0:
	s_load_dwordx2 s[8:9], s[0:1], 0x88
	s_mov_b32 s14, s10
	s_mul_hi_u32 s15, s14, 0x2e8ba2f
	s_mul_i32 s16, s15, 88
	s_sub_u32 s16, s14, s16
	s_mul_i32 s17, s15, 0xb0000
	s_lshl_b32 s19, s16, 7
	s_add_u32 s17, s17, s19
	s_mov_b32 s3, 0x2c00
	s_mul_i32 s46, s16, 0x20000
	s_lshl_b32 s47, s15, 7
	s_add_u32 s46, s46, s47
	s_add_u32 s46, s46, 0x1000000
	s_add_u32 s34, s22, s46
	s_addc_u32 s35, s23, 0
	s_mov_b32 s36, 0x800
	s_mov_b64 s[38:39], -1

; #define LAS __attribute__((address_space(3)))
; __device__ __forceinline__ void conv_mat(const float* W, const float* g, int ldw, int K, int ncols, bf16* WT, int mode, int roff, LAS float* scr, int lane, int gw, int NGW) {
;     const int nitems = (K / 64) * (ncols / 32);
;     for (int it = gw; it < nitems; it += NGW) transpose_item(W, g, ldw, K, ncols, WT, mode, roff, scr, it, lane);
; }
; __device__ __forceinline__ void conv_w13(const float* w1, const float* w3, const float* g, unsigned char* ws, LAS float* scr, int lane, int gw, int NGW) {
;     bf16* W13 = (bf16*)(ws + WS_W13);
;     conv_mat(w1, g, DFF, DM, DFF, W13, 1, 0, scr, lane, gw, NGW);
;     conv_mat(w3, g, DFF, DM, DFF, W13, 1, 16, scr, lane, (gw + NGW / 2) % NGW, NGW);
; }
.Lcw_p3t_loop:
	s_add_u32 s10, s10, s11
	s_cmp_lt_u32 s10, 2816
	s_cbranch_scc0 .Lcw_p3t_lastA
	s_cmp_lt_u32 s10, 1408
	s_cbranch_scc1 .Lcw_p3t_i1_c0
.Lcw_p3t_i1_c1:
	s_load_dwordx2 s[8:9], s[0:1], 0x90
	s_sub_u32 s14, s10, 1408
	s_mul_hi_u32 s15, s14, 0x2e8ba2f
	s_mul_i32 s16, s15, 88
	s_sub_u32 s16, s14, s16
	s_mul_i32 s17, s15, 0xb0000
	s_lshl_b32 s19, s16, 7
	s_add_u32 s17, s17, s19
	s_mov_b32 s3, 0x2c00
	s_mul_i32 s46, s16, 0x20000
	s_lshl_b32 s47, s15, 7
	s_add_u32 s46, s46, s47
	s_add_u32 s46, s46, 0x1008000
	s_add_u32 s40, s22, s46
	s_addc_u32 s41, s23, 0
	s_mov_b32 s42, 0x800
	s_mov_b64 s[44:45], -1
	s_branch .Lcw_p3t_i1_go
.Lcw_p3t_i1_c0:
	s_load_dwordx2 s[8:9], s[0:1], 0x88
	s_mov_b32 s14, s10
	s_mul_hi_u32 s15, s14, 0x2e8ba2f
	s_mul_i32 s16, s15, 88
	s_sub_u32 s16, s14, s16
	s_mul_i32 s17, s15, 0xb0000
	s_lshl_b32 s19, s16, 7
	s_add_u32 s17, s17, s19
	s_mov_b32 s3, 0x2c00
	s_mul_i32 s46, s16, 0x20000
	s_lshl_b32 s47, s15, 7
	s_add_u32 s46, s46, s47
	s_add_u32 s46, s46, 0x1000000
	s_add_u32 s40, s22, s46
	s_addc_u32 s41, s23, 0
	s_mov_b32 s42, 0x800
	s_mov_b64 s[44:45], -1

; #define GAS __attribute__((address_space(1)))
; #define LAS __attribute__((address_space(3)))
; #define LDS_WAIT() asm volatile("s_waitcnt lgkmcnt(0)" ::: "memory")
; __device__ __forceinline__ unsigned pk2(float lo, float hi) { const f32x2_t_ v = {lo, hi}; return __builtin_bit_cast(unsigned, __builtin_convertvector(v, bf16x2_t_)); }
; __device__ __forceinline__ void transpose_item(const float* W, const float* g, int ldw, int K, int ncols, bf16* WT, int mode, int roff, LAS float* scr, int item, int lane) {
;     ...
;     for (int i = 0; i < 32; ++i) { const int kk = 2 * i + (lane >> 5); scr[kk * 33 + (lane & 31)] = W[(size_t)(k0 + kk) * ldw + n0 + (lane & 31)] * __shfl(g0, kk); }
;     LDS_WAIT(); asm volatile("" ::: "memory");
;     const int c = lane & 7;
; #pragma unroll
;     for (int j = 0; j < 4; ++j) { const int n = (lane >> 3) + 8 * j; const LAS float* s = scr + (8 * c) * 33 + n;
;         v4u o; o.x = pk2(s[0 * 33], s[1 * 33]); o.y = pk2(s[2 * 33], s[3 * 33]); o.z = pk2(s[4 * 33], s[5 * 33]); o.w = pk2(s[6 * 33], s[7 * 33]);
;         const int jc = n0 + n; const int drow = mode ? roff + ((jc >> 4) << 5) + (jc & 15) : roff + jc;
;         *(GAS v4u*)(WT + (size_t)drow * K + k0 + 8 * c) = o; }
;     LDS_WAIT(); asm volatile("" ::: "memory");
.Lcw_p3t_pA:
	s_mov_b32 s13, 0
	ds_write_b32 v4, v16
	ds_write_b32 v4, v17 offset:4
	ds_write_b32 v4, v18 offset:8
	ds_write_b32 v4, v19 offset:12
	ds_write_b32 v4, v20 offset:1056
	ds_write_b32 v4, v21 offset:1060
	ds_write_b32 v4, v22 offset:1064
	ds_write_b32 v4, v23 offset:1068
	ds_write_b32 v4, v24 offset:2112
	ds_write_b32 v4, v25 offset:2116
	ds_write_b32 v4, v26 offset:2120
	ds_write_b32 v4, v27 offset:2124
	ds_write_b32 v4, v28 offset:3168
	ds_write_b32 v4, v29 offset:3172
	ds_write_b32 v4, v30 offset:3176
	ds_write_b32 v4, v31 offset:3180
	ds_write_b32 v4, v32 offset:4224
	ds_write_b32 v4, v33 offset:4228
	ds_write_b32 v4, v34 offset:4232
	ds_write_b32 v4, v35 offset:4236
	ds_write_b32 v4, v36 offset:5280
	ds_write_b32 v4, v37 offset:5284
	ds_write_b32 v4, v38 offset:5288
	ds_write_b32 v4, v39 offset:5292
	ds_write_b32 v4, v40 offset:6336
	ds_write_b32 v4, v41 offset:6340
	ds_write_b32 v4, v42 offset:6344
	ds_write_b32 v4, v43 offset:6348
	ds_write_b32 v4, v44 offset:7392
	ds_write_b32 v4, v45 offset:7396
	ds_write_b32 v4, v46 offset:7400
	ds_write_b32 v4, v47 offset:7404
	v_cndmask_b32_e64 v15, v6, v10, s[38:39]
	v_mad_u32_u24 v128, v15, s36, v3
	v_cndmask_b32_e64 v15, v7, v11, s[38:39]
	v_mad_u32_u24 v129, v15, s36, v3
	v_cndmask_b32_e64 v15, v8, v12, s[38:39]
	v_mad_u32_u24 v130, v15, s36, v3
	v_cndmask_b32_e64 v15, v9, v13, s[38:39]
	v_mad_u32_u24 v131, v15, s36, v3
	s_waitcnt lgkmcnt(0)
	ds_read2_b32 v[80:81], v5 offset0:0 offset1:33
	ds_read2_b32 v[82:83], v5 offset0:66 offset1:99
	ds_read2_b32 v[84:85], v5 offset0:132 offset1:165
	ds_read2_b32 v[86:87], v5 offset0:198 offset1:231
	ds_read2_b32 v[88:89], v5 offset0:8 offset1:41
	ds_read2_b32 v[90:91], v5 offset0:74 offset1:107
	ds_read2_b32 v[92:93], v5 offset0:140 offset1:173
	ds_read2_b32 v[94:95], v5 offset0:206 offset1:239
	ds_read2_b32 v[96:97], v5 offset0:16 offset1:49
	ds_read2_b32 v[98:99], v5 offset0:82 offset1:115
	ds_read2_b32 v[100:101], v5 offset0:148 offset1:181
	ds_read2_b32 v[102:103], v5 offset0:214 offset1:247
	ds_read2_b32 v[104:105], v5 offset0:24 offset1:57
	ds_read2_b32 v[106:107], v5 offset0:90 offset1:123
	ds_read2_b32 v[108:109], v5 offset0:156 offset1:189
	ds_read2_b32 v[110:111], v5 offset0:222 offset1:255
	s_waitcnt lgkmcnt(12)
	v_cvt_pk_bf16_f32 v112, v80, v81
	v_cvt_pk_bf16_f32 v113, v82, v83
	v_cvt_pk_bf16_f32 v114, v84, v85
	v_cvt_pk_bf16_f32 v115, v86, v87
	global_store_dwordx4 v128, v[112:115], s[34:35]
	s_waitcnt lgkmcnt(8)
	v_cvt_pk_bf16_f32 v116, v88, v89
	v_cvt_pk_bf16_f32 v117, v90, v91
	v_cvt_pk_bf16_f32 v118, v92, v93
	v_cvt_pk_bf16_f32 v119, v94, v95
	global_store_dwordx4 v129, v[116:119], s[34:35]
	s_waitcnt lgkmcnt(4)
	v_cvt_pk_bf16_f32 v120, v96, v97
	v_cvt_pk_bf16_f32 v121, v98, v99
	v_cvt_pk_bf16_f32 v122, v100, v101
	v_cvt_pk_bf16_f32 v123, v102, v103
	global_store_dwordx4 v130, v[120:123], s[34:35]
	s_waitcnt lgkmcnt(0)
	v_cvt_pk_bf16_f32 v124, v104, v105
	v_cvt_pk_bf16_f32 v125, v106, v107
	v_cvt_pk_bf16_f32 v126, v108, v109
	v_cvt_pk_bf16_f32 v127, v110, v111
	global_store_dwordx4 v131, v[124:127], s[34:35]
	s_add_u32 s10, s10, s11
	s_cmp_lt_u32 s10, 2816
	s_cbranch_scc0 .Lcw_p3t_lastB
	s_cmp_lt_u32 s10, 1408
	s_cbranch_scc1 .Lcw_p3t_i2_c0

; __device__ __forceinline__ unsigned xb_ld(unsigned* p)              { return __hip_atomic_load(p, __ATOMIC_RELAXED, __HIP_MEMORY_SCOPE_AGENT); }
; __device__ __forceinline__ unsigned xb_add(unsigned* p, unsigned v) { return __hip_atomic_fetch_add(p, v, __ATOMIC_RELAXED, __HIP_MEMORY_SCOPE_AGENT); }
; __device__ __forceinline__ void xcd_barrier_complete(unsigned* bar, unsigned x, unsigned& nloc, unsigned& nx) {
;     const unsigned G = gridDim.x * gridDim.y * gridDim.z;
;     unsigned sum, cnt, mine, sp = 0u;
;     for (;;) {
;         sum = 0u; cnt = 0u; mine = 0u;
; #pragma unroll
;         for (unsigned j = 0; j < 16; ++j) { const unsigned c = xb_ld(&bar[XB_XCNT(j)]); sum += c; cnt += (c > 0u) ? 1u : 0u; mine = (j == x) ? c : mine; }
; __device__ __forceinline__ void xcd_barrier(const XcdBarrier& b) {
;     asm volatile("s_waitcnt vmcnt(0)" ::: "memory");
;     __syncthreads();
;     if (threadIdx.x == 0) {
;         unsigned* bar = b.bar;
;         __builtin_amdgcn_s_waitcnt(0);
;         unsigned nloc = b.st[0], nx = b.st[1];
;         if (nloc == 0u) { xcd_barrier_complete(bar, b.x, nloc, nx); b.st[0] = nloc; b.st[1] = nx; }
;         const unsigned old = xb_add(&bar[XB_XSUB(b.x)], 1u);
.Lcw_p3t_done:
	s_waitcnt lgkmcnt(0)
.Lcm_p3t_skip:
	s_waitcnt vmcnt(0)
	s_waitcnt vmcnt(0)
	s_barrier
	s_and_saveexec_b64 s[6:7], s[4:5]
	s_cbranch_execz .LBB0_978
	s_add_i32 s3, 0, 0x20160
	v_mov_b32_e32 v1, s3
	s_waitcnt vmcnt(0) expcnt(0) lgkmcnt(0)
	ds_read_b32 v3, v1
	s_add_i32 s3, 0, 0x20164
	v_mov_b32_e32 v1, s3
	ds_read_b32 v1, v1
	s_waitcnt lgkmcnt(1)
	v_cmp_ne_u32_e32 vcc, 0, v3
	s_cbranch_vccnz .LBB0_885
	s_load_dwordx2 s[12:13], s[26:27], 0x4
	s_add_u32 s8, s22, 0x4200
	s_addc_u32 s9, s23, 0
	s_add_u32 s10, s22, 0x4400
	s_addc_u32 s11, s23, 0
	s_waitcnt lgkmcnt(0)
	s_mul_i32 s3, s12, s18
	s_add_u32 s12, s22, 0x4500
	s_mul_i32 s3, s3, s13
	s_addc_u32 s13, s23, 0
	s_add_u32 s14, s22, 0x4600
	s_addc_u32 s15, s23, 0
	s_add_u32 s16, s22, 0x4700
	s_addc_u32 s17, s23, 0
	s_add_u32 s36, s22, 0x4800
	s_addc_u32 s37, s23, 0
	s_add_u32 s38, s22, 0x4900
	s_addc_u32 s39, s23, 0
	s_add_u32 s40, s22, 0x4a00
	s_addc_u32 s41, s23, 0
	s_add_u32 s42, s22, 0x4b00
	s_addc_u32 s43, s23, 0
	s_add_u32 s44, s22, 0x4c00
	s_addc_u32 s45, s23, 0
	s_add_u32 s46, s22, 0x4d00
	s_addc_u32 s47, s23, 0
	s_add_u32 s48, s22, 0x4e00
	s_addc_u32 s49, s23, 0
	s_add_u32 s50, s22, 0x4f00
	s_addc_u32 s51, s23, 0
	s_add_u32 s52, s22, 0x5000
	s_addc_u32 s53, s23, 0
	s_add_u32 s54, s22, 0x5100
	s_addc_u32 s55, s23, 0
	s_add_u32 s56, s22, 0x5200
	s_addc_u32 s57, s23, 0
	s_add_u32 s58, s22, 0x5300
	s_addc_u32 s59, s23, 0
	s_mov_b32 s19, 1
	v_mov_b32_e32 v17, 0
	s_branch .LBB0_873

; __device__ __forceinline__ const float* kin(int k) { KArgs p = (KArgs)__builtin_amdgcn_kernarg_segment_ptr(); asm volatile("" : "+s"(p)); return p->in[k]; }
; __global__ void __launch_bounds__(NWAVES * 64, 2) mk_fwd(Args args) {
;     ...
;                 zb_rows(ws, kin(11), st_c, out, F.lane, cgw, CNGW);
;                 conv_mat(kin(13), nullptr, DM, DA, DM, (bf16*)(ws + WS_WA), 0, 0, SCR_, F.lane, cgw, CNGW);
;                 conv_mat(kin(14), nullptr, DM, DA, DM, (bf16*)(ws + WS_WB), 0, 0, SCR_, F.lane, (cgw + CNGW / 4) % CNGW, CNGW);
;                 conv_mat(kin(15), nullptr, DM, DM, DM, (bf16*)(ws + WS_WO), 0, 0, SCR_, F.lane, (cgw + CNGW / 2) % CNGW, CNGW);
;                 conv_w13(kin(17), kin(18), nullptr, ws, SCR_, F.lane, cgw, CNGW);
;                 conv_w2(kin(19), ws, SCR_, F.lane, (cgw + CNGW / 3) % CNGW, CNGW);
.LBB0_1163:
	s_or_b64 exec, exec, s[16:17]
.LBB0_1193:
	s_mov_b64 s[6:7], 0

; #define GAS __attribute__((address_space(1)))
; #define LAS __attribute__((address_space(3)))
; #define LDS_WAIT() asm volatile("s_waitcnt lgkmcnt(0)" ::: "memory")
; __device__ __forceinline__ unsigned pk2(float lo, float hi) { const f32x2_t_ v = {lo, hi}; return __builtin_bit_cast(unsigned, __builtin_convertvector(v, bf16x2_t_)); }
; __device__ __forceinline__ void transpose_item(const float* W, const float* g, int ldw, int K, int ncols, bf16* WT, int mode, int roff, LAS float* scr, int item, int lane) {
;     const int nblk = ncols / 32, kb = item / nblk, nb = item % nblk, k0 = 64 * kb, n0 = 32 * nb;
;     const float g0 = g ? g[k0 + lane] : 1.0f;
; #pragma unroll 8
;     for (int i = 0; i < 32; ++i) { const int kk = 2 * i + (lane >> 5); scr[kk * 33 + (lane & 31)] = W[(size_t)(k0 + kk) * ldw + n0 + (lane & 31)] * __shfl(g0, kk); }
;     LDS_WAIT(); asm volatile("" ::: "memory");
;     const int c = lane & 7;
; #pragma unroll
;     for (int j = 0; j < 4; ++j) { const int n = (lane >> 3) + 8 * j; const LAS float* s = scr + (8 * c) * 33 + n;
;         v4u o; o.x = pk2(s[0 * 33], s[1 * 33]); o.y = pk2(s[2 * 33], s[3 * 33]); o.z = pk2(s[4 * 33], s[5 * 33]); o.w = pk2(s[6 * 33], s[7 * 33]);
;         const int jc = n0 + n; const int drow = mode ? roff + ((jc >> 4) << 5) + (jc & 15) : roff + jc;
;         *(GAS v4u*)(WT + (size_t)drow * K + k0 + 8 * c) = o; }
;     LDS_WAIT(); asm volatile("" ::: "memory");
; }
; __device__ __forceinline__ void conv_mat(const float* W, const float* g, int ldw, int K, int ncols, bf16* WT, int mode, int roff, LAS float* scr, int lane, int gw, int NGW) {
;     const int nitems = (K / 64) * (ncols / 32);
;     for (int it = gw; it < nitems; it += NGW) transpose_item(W, g, ldw, K, ncols, WT, mode, roff, scr, it, lane);
; }
.LBB0_1821:
	s_cmpk_lt_i32 s2, 0xd8
	s_cbranch_scc1 .Lcm_p7t_skip
	s_mov_b64 exec, -1
	v_readfirstlane_b32 s3, v0
	s_lshr_b32 s3, s3, 6
	s_lshl_b32 s12, s3, 14
	s_sub_i32 s10, s2, 0xd8
	s_lshl_b32 s10, s10, 3
	s_add_i32 s10, s10, s3
	s_sub_i32 s11, s18, 0xd8
	s_lshl_b32 s11, s11, 3
	v_and_b32_e32 v15, 63, v0
	v_lshrrev_b32_e32 v2, 3, v15
	v_and_b32_e32 v3, 7, v15
	v_lshlrev_b32_e32 v3, 4, v3
	v_mul_u32_u24_e32 v4, 0x84, v2
	v_add3_u32 v4, v4, v3, s12
	v_and_b32_e32 v5, 7, v15
	v_mul_u32_u24_e32 v5, 0x420, v5
	v_lshl_add_u32 v5, v2, 2, v5
	v_add_u32_e32 v5, s12, v5
	v_add_u32_e32 v6, 0, v2
	v_lshrrev_b32_e32 v10, 4, v6
	v_lshlrev_b32_e32 v10, 5, v10
	v_and_b32_e32 v14, 15, v6
	v_or_b32_e32 v10, v10, v14
	v_add_u32_e32 v7, 8, v2
	v_lshrrev_b32_e32 v11, 4, v7
	v_lshlrev_b32_e32 v11, 5, v11
	v_and_b32_e32 v14, 15, v7
	v_or_b32_e32 v11, v11, v14
	v_add_u32_e32 v8, 16, v2
	v_lshrrev_b32_e32 v12, 4, v8
	v_lshlrev_b32_e32 v12, 5, v12
	v_and_b32_e32 v14, 15, v8
	v_or_b32_e32 v12, v12, v14
	v_add_u32_e32 v9, 24, v2
	v_lshrrev_b32_e32 v13, 4, v9
	v_lshlrev_b32_e32 v13, 5, v13
	v_and_b32_e32 v14, 15, v9
	v_or_b32_e32 v13, v13, v14
	s_cmp_lt_u32 s10, 1408
	s_cbranch_scc0 .Lcw_p7t_done
.Lcw_p7t_i0_c0:
	s_load_dwordx2 s[8:9], s[0:1], 0x98
	s_mov_b32 s14, s10
	s_lshr_b32 s15, s14, 5
	s_and_b32 s16, s14, 31
	s_mul_i32 s17, s15, 0x40000
	s_lshl_b32 s19, s16, 7
	s_add_u32 s17, s17, s19
	s_mov_b32 s3, 0x1000
	s_mul_i32 s46, s16, 0x2c000
	s_lshl_b32 s47, s15, 7
	s_add_u32 s46, s46, s47
	s_add_u32 s46, s46, 0x1b00000
	s_add_u32 s34, s22, s46
	s_addc_u32 s35, s23, 0
	s_mov_b32 s36, 0x1600
	s_mov_b64 s[38:39], 0

; #define LAS __attribute__((address_space(3)))
; __device__ __forceinline__ void transpose_item(const float* W, const float* g, int ldw, int K, int ncols, bf16* WT, int mode, int roff, LAS float* scr, int item, int lane) {
;     const int nblk = ncols / 32, kb = item / nblk, nb = item % nblk, k0 = 64 * kb, n0 = 32 * nb;
; __device__ __forceinline__ void conv_mat(const float* W, const float* g, int ldw, int K, int ncols, bf16* WT, int mode, int roff, LAS float* scr, int lane, int gw, int NGW) {
;     const int nitems = (K / 64) * (ncols / 32);
;     for (int it = gw; it < nitems; it += NGW) transpose_item(W, g, ldw, K, ncols, WT, mode, roff, scr, it, lane);
; }
.Lcw_p7t_loop:
	s_add_u32 s10, s10, s11
	s_cmp_lt_u32 s10, 1408
	s_cbranch_scc0 .Lcw_p7t_lastA
.Lcw_p7t_i1_c0:
	s_load_dwordx2 s[8:9], s[0:1], 0x98
	s_mov_b32 s14, s10
	s_lshr_b32 s15, s14, 5
	s_and_b32 s16, s14, 31
	s_mul_i32 s17, s15, 0x40000
	s_lshl_b32 s19, s16, 7
	s_add_u32 s17, s17, s19
	s_mov_b32 s3, 0x1000
	s_mul_i32 s46, s16, 0x2c000
	s_lshl_b32 s47, s15, 7
	s_add_u32 s46, s46, s47
	s_add_u32 s46, s46, 0x1b00000
	s_add_u32 s40, s22, s46
	s_addc_u32 s41, s23, 0
	s_mov_b32 s42, 0x1600
	s_mov_b64 s[44:45], 0

; #define GAS __attribute__((address_space(1)))
; #define LAS __attribute__((address_space(3)))
; #define LDS_WAIT() asm volatile("s_waitcnt lgkmcnt(0)" ::: "memory")
; __device__ __forceinline__ unsigned pk2(float lo, float hi) { const f32x2_t_ v = {lo, hi}; return __builtin_bit_cast(unsigned, __builtin_convertvector(v, bf16x2_t_)); }
; __device__ __forceinline__ void transpose_item(const float* W, const float* g, int ldw, int K, int ncols, bf16* WT, int mode, int roff, LAS float* scr, int item, int lane) {
;     ...
;     const float g0 = g ? g[k0 + lane] : 1.0f;
; #pragma unroll 8
;     for (int i = 0; i < 32; ++i) { const int kk = 2 * i + (lane >> 5); scr[kk * 33 + (lane & 31)] = W[(size_t)(k0 + kk) * ldw + n0 + (lane & 31)] * __shfl(g0, kk); }
;     LDS_WAIT(); asm volatile("" ::: "memory");
;     const int c = lane & 7;
; #pragma unroll
;     for (int j = 0; j < 4; ++j) { const int n = (lane >> 3) + 8 * j; const LAS float* s = scr + (8 * c) * 33 + n;
;         v4u o; o.x = pk2(s[0 * 33], s[1 * 33]); o.y = pk2(s[2 * 33], s[3 * 33]); o.z = pk2(s[4 * 33], s[5 * 33]); o.w = pk2(s[6 * 33], s[7 * 33]);
;         const int jc = n0 + n; const int drow = mode ? roff + ((jc >> 4) << 5) + (jc & 15) : roff + jc;
;         *(GAS v4u*)(WT + (size_t)drow * K + k0 + 8 * c) = o; }
;     LDS_WAIT(); asm volatile("" ::: "memory");
; }
.Lcw_p7t_pA:
	s_mov_b32 s13, 0
	ds_write_b32 v4, v16
	ds_write_b32 v4, v17 offset:4
	ds_write_b32 v4, v18 offset:8
	ds_write_b32 v4, v19 offset:12
	ds_write_b32 v4, v20 offset:1056
	ds_write_b32 v4, v21 offset:1060
	ds_write_b32 v4, v22 offset:1064
	ds_write_b32 v4, v23 offset:1068
	ds_write_b32 v4, v24 offset:2112
	ds_write_b32 v4, v25 offset:2116
	ds_write_b32 v4, v26 offset:2120
	ds_write_b32 v4, v27 offset:2124
	ds_write_b32 v4, v28 offset:3168
	ds_write_b32 v4, v29 offset:3172
	ds_write_b32 v4, v30 offset:3176
	ds_write_b32 v4, v31 offset:3180
	ds_write_b32 v4, v32 offset:4224
	ds_write_b32 v4, v33 offset:4228
	ds_write_b32 v4, v34 offset:4232
	ds_write_b32 v4, v35 offset:4236
	ds_write_b32 v4, v36 offset:5280
	ds_write_b32 v4, v37 offset:5284
	ds_write_b32 v4, v38 offset:5288
	ds_write_b32 v4, v39 offset:5292
	ds_write_b32 v4, v40 offset:6336
	ds_write_b32 v4, v41 offset:6340
	ds_write_b32 v4, v42 offset:6344
	ds_write_b32 v4, v43 offset:6348
	ds_write_b32 v4, v44 offset:7392
	ds_write_b32 v4, v45 offset:7396
	ds_write_b32 v4, v46 offset:7400
	ds_write_b32 v4, v47 offset:7404
	v_cndmask_b32_e64 v15, v6, v10, s[38:39]
	v_mad_u32_u24 v128, v15, s36, v3
	v_cndmask_b32_e64 v15, v7, v11, s[38:39]
	v_mad_u32_u24 v129, v15, s36, v3
	v_cndmask_b32_e64 v15, v8, v12, s[38:39]
	v_mad_u32_u24 v130, v15, s36, v3
	v_cndmask_b32_e64 v15, v9, v13, s[38:39]
	v_mad_u32_u24 v131, v15, s36, v3
	s_waitcnt lgkmcnt(0)
	ds_read2_b32 v[80:81], v5 offset0:0 offset1:33
	ds_read2_b32 v[82:83], v5 offset0:66 offset1:99
	ds_read2_b32 v[84:85], v5 offset0:132 offset1:165
	ds_read2_b32 v[86:87], v5 offset0:198 offset1:231
	ds_read2_b32 v[88:89], v5 offset0:8 offset1:41
	ds_read2_b32 v[90:91], v5 offset0:74 offset1:107
	ds_read2_b32 v[92:93], v5 offset0:140 offset1:173
	ds_read2_b32 v[94:95], v5 offset0:206 offset1:239
	ds_read2_b32 v[96:97], v5 offset0:16 offset1:49
	ds_read2_b32 v[98:99], v5 offset0:82 offset1:115
	ds_read2_b32 v[100:101], v5 offset0:148 offset1:181
	ds_read2_b32 v[102:103], v5 offset0:214 offset1:247
	ds_read2_b32 v[104:105], v5 offset0:24 offset1:57
	ds_read2_b32 v[106:107], v5 offset0:90 offset1:123
	ds_read2_b32 v[108:109], v5 offset0:156 offset1:189
	ds_read2_b32 v[110:111], v5 offset0:222 offset1:255
	s_waitcnt lgkmcnt(12)
	v_cvt_pk_bf16_f32 v112, v80, v81
	v_cvt_pk_bf16_f32 v113, v82, v83
	v_cvt_pk_bf16_f32 v114, v84, v85
	v_cvt_pk_bf16_f32 v115, v86, v87
	global_store_dwordx4 v128, v[112:115], s[34:35]
	s_waitcnt lgkmcnt(8)
	v_cvt_pk_bf16_f32 v116, v88, v89
	v_cvt_pk_bf16_f32 v117, v90, v91
	v_cvt_pk_bf16_f32 v118, v92, v93
	v_cvt_pk_bf16_f32 v119, v94, v95
	global_store_dwordx4 v129, v[116:119], s[34:35]
	s_waitcnt lgkmcnt(4)
	v_cvt_pk_bf16_f32 v120, v96, v97
	v_cvt_pk_bf16_f32 v121, v98, v99
	v_cvt_pk_bf16_f32 v122, v100, v101
	v_cvt_pk_bf16_f32 v123, v102, v103
	global_store_dwordx4 v130, v[120:123], s[34:35]
	s_waitcnt lgkmcnt(0)
	v_cvt_pk_bf16_f32 v124, v104, v105
	v_cvt_pk_bf16_f32 v125, v106, v107
	v_cvt_pk_bf16_f32 v126, v108, v109
	v_cvt_pk_bf16_f32 v127, v110, v111
	global_store_dwordx4 v131, v[124:127], s[34:35]
	s_add_u32 s10, s10, s11
	s_cmp_lt_u32 s10, 1408
	s_cbranch_scc0 .Lcw_p7t_lastB

; __device__ __forceinline__ unsigned xb_ld(unsigned* p)              { return __hip_atomic_load(p, __ATOMIC_RELAXED, __HIP_MEMORY_SCOPE_AGENT); }
; __device__ __forceinline__ void xcd_barrier_complete(unsigned* bar, unsigned x, unsigned& nloc, unsigned& nx) {
;     const unsigned G = gridDim.x * gridDim.y * gridDim.z;
;     unsigned sum, cnt, mine, sp = 0u;
;     for (;;) {
;         sum = 0u; cnt = 0u; mine = 0u;
; #pragma unroll
;         for (unsigned j = 0; j < 16; ++j) { const unsigned c = xb_ld(&bar[XB_XCNT(j)]); sum += c; cnt += (c > 0u) ? 1u : 0u; mine = (j == x) ? c : mine; }
; __device__ __forceinline__ void xcd_barrier(const XcdBarrier& b) {
;     asm volatile("s_waitcnt vmcnt(0)" ::: "memory");
;     __syncthreads();
;     if (threadIdx.x == 0) {
;         unsigned* bar = b.bar;
;         __builtin_amdgcn_s_waitcnt(0);
;         unsigned nloc = b.st[0], nx = b.st[1];
;         if (nloc == 0u) { xcd_barrier_complete(bar, b.x, nloc, nx); b.st[0] = nloc; b.st[1] = nx; }
.Lcw_p7t_done:
	s_waitcnt lgkmcnt(0)
.Lcm_p7t_skip:
	s_waitcnt vmcnt(0)
	s_waitcnt vmcnt(0)
	s_barrier
	s_and_saveexec_b64 s[6:7], s[4:5]
	s_cbranch_execz .LBB0_1873
	s_add_i32 s3, 0, 0x20160
	v_mov_b32_e32 v2, s3
	s_waitcnt vmcnt(0) expcnt(0) lgkmcnt(0)
	ds_read_b32 v4, v2
	s_add_i32 s3, 0, 0x20164
	v_mov_b32_e32 v2, s3
	ds_read_b32 v2, v2
	s_waitcnt lgkmcnt(1)
	v_cmp_ne_u32_e32 vcc, 0, v4
	s_cbranch_vccnz .LBB0_1837
	s_load_dwordx2 s[12:13], s[26:27], 0x4
	s_add_u32 s8, s22, 0x4200
	s_addc_u32 s9, s23, 0
	s_add_u32 s10, s22, 0x4400
	s_addc_u32 s11, s23, 0
	s_waitcnt lgkmcnt(0)
	s_mul_i32 s3, s12, s18
	s_add_u32 s12, s22, 0x4500
	s_mul_i32 s3, s3, s13
	s_addc_u32 s13, s23, 0
	s_add_u32 s14, s22, 0x4600
	s_addc_u32 s15, s23, 0
	s_add_u32 s16, s22, 0x4700
	s_addc_u32 s17, s23, 0
	s_add_u32 s30, s22, 0x4800
	s_addc_u32 s31, s23, 0
	s_add_u32 s34, s22, 0x4900
	s_addc_u32 s35, s23, 0
	s_add_u32 s36, s22, 0x4a00
	s_addc_u32 s37, s23, 0
	s_add_u32 s38, s22, 0x4b00
	s_addc_u32 s39, s23, 0
	s_add_u32 s40, s22, 0x4c00
	s_addc_u32 s41, s23, 0
	s_add_u32 s42, s22, 0x4d00
	s_addc_u32 s43, s23, 0
	s_add_u32 s44, s22, 0x4e00
	s_addc_u32 s45, s23, 0
	s_add_u32 s46, s22, 0x4f00
	s_addc_u32 s47, s23, 0
	s_add_u32 s48, s22, 0x5000
	s_addc_u32 s49, s23, 0
	s_add_u32 s50, s22, 0x5100
	s_addc_u32 s51, s23, 0
	s_add_u32 s52, s22, 0x5200
	s_addc_u32 s53, s23, 0
	s_add_u32 s54, s22, 0x5300
	s_addc_u32 s55, s23, 0
	s_mov_b32 s19, 1
	v_mov_b32_e32 v18, 0
	s_branch .LBB0_1825
